# prep wave: next-chunk row loads interleaved into the position math instead of one burst at the loop top
# speedup vs baseline: 1.0167x; 1.0012x over previous
.LBB0_597:
	s_andn2_b64 vcc, exec, s[36:37]
	s_cbranch_vccnz .LBB0_594
	ds_read2st64_b32 v[236:237], v210 offset1:1
	ds_read2st64_b32 v[238:239], v210 offset0:2 offset1:3
	ds_read2st64_b32 v[240:241], v210 offset0:4 offset1:5
	ds_read2st64_b32 v[242:243], v210 offset0:6 offset1:7
	ds_read2st64_b32 v[244:245], v210 offset0:8 offset1:9
	ds_read2st64_b32 v[246:247], v210 offset0:10 offset1:11
	ds_read2st64_b32 v[248:249], v210 offset0:12 offset1:13
	ds_read2st64_b32 v[250:251], v210 offset0:14 offset1:15
	s_add_i32 s83, s0, 1
	s_cmp_lt_u32 s83, s63
	s_cselect_b32 s0, s83, s0
	s_lshl_b32 s3, s0, 3
	s_sub_i32 s17, s61, s3
	s_and_b64 s[0:1], s[12:13], exec
	s_cselect_b32 s84, s3, s17
	s_add_i32 s3, s84, -1
	s_cmp_lt_u32 s3, s62
	s_cselect_b64 vcc, -1, 0
	s_and_b64 s[0:1], vcc, exec
	s_cselect_b32 s0, s3, s84
	s_add_i32 s0, s0, s14
	v_add_u32_e32 v64, s84, v133
	v_mad_i64_i32 v[100:101], s[0:1], s0, v212, v[96:97]
	v_ashrrev_i32_e32 v65, 31, v64
	s_add_i32 s99, s84, s14
	s_or_b32 s98, s84, 1
	v_lshlrev_b64 v[64:65], 11, v[64:65]
	s_cmp_lt_u32 s98, s62
	v_lshl_add_u64 v[72:73], v[200:201], 0, v[64:65]
	s_cselect_b64 s[36:37], -1, 0
	global_load_dwordx4 v[88:91], v[72:73], off offset:272
	global_load_dwordx4 v[92:95], v[72:73], off offset:256
	global_load_dwordx4 v[68:71], v[72:73], off offset:784
	global_load_dwordx4 v[84:87], v[72:73], off offset:768
	global_load_dwordx4 v[76:79], v[72:73], off offset:400
	global_load_dwordx4 v[80:83], v[72:73], off offset:384
	global_load_dwordx4 v[64:67], v[72:73], off offset:912
	s_nop 0
	global_load_dwordx4 v[72:75], v[72:73], off offset:896
	s_nop 0
	global_load_short_d16_hi v134, v[100:101], off
	global_load_short_d16_hi v135, v[100:101], off offset:128
	global_load_short_d16_hi v136, v[100:101], off offset:256
	v_mul_f32_e32 v102, v119, v180
	v_fmac_f32_e32 v102, v118, v178
	v_fmac_f32_e32 v102, v120, v105
	v_mul_f32_e32 v178, v125, v102
	v_mul_f32_e32 v100, v178, v178
	v_mov_b32_e32 v101, v185
	v_mul_f32_e32 v176, v116, v181
	v_fmac_f32_e32 v176, v124, v182
	v_mov_b32_dpp v101, v100 quad_perm:[1,0,3,2] row_mask:0xf bank_mask:0xf
	v_fmac_f32_e32 v101, v178, v178
	v_fmac_f32_e32 v176, v117, v177
	v_mov_b32_e32 v103, v185
	v_add_f32_dpp v100, v101, v101 quad_perm:[2,3,0,1] row_mask:0xf bank_mask:0xf bound_ctrl:1
	s_and_b64 s[0:1], s[12:13], exec
	s_cselect_b32 s21, s15, s74
	v_add_f32_dpp v100, v100, v100 row_half_mirror row_mask:0xf bank_mask:0xf bound_ctrl:1
	s_add_i32 s21, s21, s14
	s_nop 0
	v_add_f32_dpp v100, v100, v100 row_mirror row_mask:0xf bank_mask:0xf bound_ctrl:1
	s_nop 0
	v_readlane_b32 s85, v100, 0
	v_readlane_b32 s20, v100, 16
	v_readlane_b32 s18, v100, 32
	v_readlane_b32 s19, v100, 48
	s_waitcnt lgkmcnt(0)
	v_add_f32_e32 v101, v129, v237
	v_mul_f32_e32 v101, 0xbfb8aa3b, v101
	v_exp_f32_e32 v101, v101
	s_nop 0
	v_add_f32_e32 v101, 1.0, v101
	v_rcp_f32_e32 v183, v101
	s_nop 0
	v_add_f32_e32 v101, -1.0, v183
	v_fma_f32 v101, v126, v101, 1.0
	v_mul_f32_e32 v182, v102, v101
	v_mul_f32_e32 v101, v176, v182
	v_mul_f32_e32 v102, v127, v101
	s_nop 1
	v_mov_b32_dpp v103, v102 quad_perm:[1,0,3,2] row_mask:0xf bank_mask:0xf
	v_fmac_f32_e32 v103, v127, v101
	v_mov_b32_e32 v102, 0
	s_nop 0
	v_add_f32_dpp v101, v103, v103 quad_perm:[2,3,0,1] row_mask:0xf bank_mask:0xf bound_ctrl:1
	s_nop 1
	v_add_f32_dpp v101, v101, v101 row_half_mirror row_mask:0xf bank_mask:0xf bound_ctrl:1
	s_nop 1
	v_mov_b32_dpp v102, v101 row_mirror row_mask:0xf bank_mask:0xf
	s_and_saveexec_b64 s[80:81], s[10:11]
	s_cbranch_execz .LBB0_600
	s_ashr_i32 s1, s21, 31
	s_add_u32 s0, s21, s88
	s_addc_u32 s1, s1, 0
	s_lshl_b64 s[0:1], s[0:1], 9
	v_lshl_add_u64 v[194:195], v[98:99], 0, s[0:1]
	v_add_f32_e32 v101, v101, v102
	global_store_dword v[194:195], v101, off
.LBB0_600:
	s_or_b64 exec, exec, s[80:81]
	v_mad_i64_i32 v[196:197], s[100:101], s99, v212, v[96:97]
	s_and_b64 s[100:101], s[36:37], exec
	s_cselect_b32 s99, s98, s84
	s_add_i32 s99, s99, s14
	s_or_b32 s98, s84, 2
	s_cmp_lt_u32 s98, s62
	s_cselect_b64 s[38:39], -1, 0
	global_load_short_d16_hi v137, v[196:197], off
	global_load_short_d16_hi v138, v[196:197], off offset:128
	global_load_short_d16_hi v139, v[196:197], off offset:256
	v_mad_i64_i32 v[196:197], s[100:101], s99, v212, v[96:97]
	s_and_b64 s[100:101], s[38:39], exec
	s_cselect_b32 s99, s98, s84
	s_add_i32 s99, s99, s14
	s_or_b32 s98, s84, 3
	s_cmp_lt_u32 s98, s62
	s_cselect_b64 s[40:41], -1, 0
	global_load_short_d16_hi v140, v[196:197], off
	global_load_short_d16_hi v141, v[196:197], off offset:128
	global_load_short_d16_hi v142, v[196:197], off offset:256
	s_and_b32 s0, s82, 4
	s_or_b32 s0, s0, s86
	v_mul_f32_e32 v102, v122, v104
	s_mulk_i32 s0, 0x3000
	v_fmac_f32_e32 v102, v121, v179
	v_add_u32_e32 v101, s0, v211
	v_fmac_f32_e32 v102, v123, v106
	ds_write_b32 v101, v102 offset:10240
	v_mul_f32_e32 v179, v116, v177
	v_fmac_f32_e32 v179, v124, v181
	v_mul_f32_e32 v181, v119, v105
	v_fmac_f32_e32 v181, v118, v180
	v_fmac_f32_e32 v181, v120, v107
	v_add_f32_e32 v103, v129, v239
	v_mul_f32_e32 v180, v125, v181
	v_mul_f32_e32 v103, 0xbfb8aa3b, v103
	v_mul_f32_e32 v184, v180, v180
	v_mov_b32_e32 v202, 0
	v_exp_f32_e32 v103, v103
	v_fmac_f32_e32 v179, v117, v175
	v_mov_b32_dpp v202, v184 quad_perm:[1,0,3,2] row_mask:0xf bank_mask:0xf
	v_fmac_f32_e32 v202, v180, v180
	v_add_f32_e32 v103, 1.0, v103
	v_mov_b32_e32 v203, 0
	v_add_f32_dpp v184, v202, v202 quad_perm:[2,3,0,1] row_mask:0xf bank_mask:0xf bound_ctrl:1
	s_nop 1
	v_add_f32_dpp v184, v184, v184 row_half_mirror row_mask:0xf bank_mask:0xf bound_ctrl:1
	s_nop 1
	v_add_f32_dpp v202, v184, v184 row_mirror row_mask:0xf bank_mask:0xf bound_ctrl:1
	v_rcp_f32_e32 v184, v103
	v_readlane_b32 s23, v202, 0
	v_readlane_b32 s25, v202, 16
	v_readlane_b32 s24, v202, 32
	v_add_f32_e32 v103, -1.0, v184
	v_fma_f32 v103, v126, v103, 1.0
	v_mul_f32_e32 v103, v181, v103
	v_mul_f32_e32 v181, v179, v103
	v_readlane_b32 s22, v202, 48
	v_mul_f32_e32 v202, v127, v181
	s_nop 1
	v_mov_b32_dpp v203, v202 quad_perm:[1,0,3,2] row_mask:0xf bank_mask:0xf
	v_fmac_f32_e32 v203, v127, v181
	v_mov_b32_e32 v202, 0
	s_nop 0
	v_add_f32_dpp v181, v203, v203 quad_perm:[2,3,0,1] row_mask:0xf bank_mask:0xf bound_ctrl:1
	s_nop 1
	v_add_f32_dpp v181, v181, v181 row_half_mirror row_mask:0xf bank_mask:0xf bound_ctrl:1
	s_nop 1
	v_mov_b32_dpp v202, v181 row_mirror row_mask:0xf bank_mask:0xf
	s_and_saveexec_b64 s[80:81], s[10:11]
	s_cbranch_execz .LBB0_602
	v_add_f32_e32 v181, v181, v202
	global_store_dword v[194:195], v181, off offset:512
.LBB0_602:
	s_or_b64 exec, exec, s[80:81]
	v_mad_i64_i32 v[196:197], s[100:101], s99, v212, v[96:97]
	s_and_b64 s[100:101], s[40:41], exec
	s_cselect_b32 s99, s98, s84
	s_add_i32 s99, s99, s14
	s_or_b32 s98, s84, 4
	s_cmp_lt_u32 s98, s62
	s_cselect_b64 s[42:43], -1, 0
	global_load_short_d16_hi v143, v[196:197], off
	global_load_short_d16_hi v144, v[196:197], off offset:128
	global_load_short_d16_hi v145, v[196:197], off offset:256
	v_mul_f32_e32 v181, v122, v106
	v_fmac_f32_e32 v181, v121, v104
	v_fmac_f32_e32 v181, v123, v108
	ds_write_b32 v101, v181 offset:10496
	v_mul_f32_e32 v181, v116, v175
	v_fmac_f32_e32 v181, v124, v177
	v_mul_f32_e32 v177, v119, v107
	v_fmac_f32_e32 v177, v118, v105
	v_fmac_f32_e32 v177, v120, v109
	v_mul_f32_e32 v202, v125, v177
	v_mul_f32_e32 v203, v202, v202
	v_mov_b32_e32 v213, 0
	v_add_f32_e32 v105, v129, v241
	v_mul_f32_e32 v105, 0xbfb8aa3b, v105
	v_exp_f32_e32 v105, v105
	v_mov_b32_dpp v213, v203 quad_perm:[1,0,3,2] row_mask:0xf bank_mask:0xf
	v_fmac_f32_e32 v213, v202, v202
	v_fmac_f32_e32 v181, v117, v174
	v_add_f32_e32 v105, 1.0, v105
	v_add_f32_dpp v203, v213, v213 quad_perm:[2,3,0,1] row_mask:0xf bank_mask:0xf bound_ctrl:1
	v_mov_b32_e32 v214, 0
	s_nop 0
	v_add_f32_dpp v203, v203, v203 row_half_mirror row_mask:0xf bank_mask:0xf bound_ctrl:1
	s_nop 1
	v_add_f32_dpp v213, v203, v203 row_mirror row_mask:0xf bank_mask:0xf bound_ctrl:1
	v_rcp_f32_e32 v203, v105
	v_readlane_b32 s26, v213, 0
	v_readlane_b32 s29, v213, 16
	v_readlane_b32 s27, v213, 32
	v_add_f32_e32 v105, -1.0, v203
	v_fma_f32 v105, v126, v105, 1.0
	v_mul_f32_e32 v105, v177, v105
	v_mul_f32_e32 v177, v181, v105
	v_readlane_b32 s28, v213, 48
	v_mul_f32_e32 v213, v127, v177
	s_nop 1
	v_mov_b32_dpp v214, v213 quad_perm:[1,0,3,2] row_mask:0xf bank_mask:0xf
	v_fmac_f32_e32 v214, v127, v177
	v_mov_b32_e32 v213, 0
	s_nop 0
	v_add_f32_dpp v177, v214, v214 quad_perm:[2,3,0,1] row_mask:0xf bank_mask:0xf bound_ctrl:1
	s_nop 1
	v_add_f32_dpp v177, v177, v177 row_half_mirror row_mask:0xf bank_mask:0xf bound_ctrl:1
	s_nop 1
	v_mov_b32_dpp v213, v177 row_mirror row_mask:0xf bank_mask:0xf
	s_and_saveexec_b64 s[80:81], s[10:11]
	s_cbranch_execz .LBB0_604
	v_add_f32_e32 v177, v177, v213
	global_store_dword v[194:195], v177, off offset:1024
.LBB0_604:
	s_or_b64 exec, exec, s[80:81]
	v_mad_i64_i32 v[196:197], s[100:101], s99, v212, v[96:97]
	s_and_b64 s[100:101], s[42:43], exec
	s_cselect_b32 s99, s98, s84
	s_add_i32 s99, s99, s14
	s_or_b32 s98, s84, 5
	s_cmp_lt_u32 s98, s62
	s_cselect_b64 s[44:45], -1, 0
	global_load_short_d16_hi v146, v[196:197], off
	global_load_short_d16_hi v147, v[196:197], off offset:128
	global_load_short_d16_hi v148, v[196:197], off offset:256
	v_mul_f32_e32 v177, v122, v108
	v_fmac_f32_e32 v177, v121, v106
	v_fmac_f32_e32 v177, v123, v110
	ds_write_b32 v101, v177 offset:10752
	v_mul_f32_e32 v177, v116, v174
	v_fmac_f32_e32 v177, v124, v175
	v_mul_f32_e32 v175, v119, v109
	v_fmac_f32_e32 v175, v118, v107
	v_fmac_f32_e32 v175, v120, v111
	v_mul_f32_e32 v213, v125, v175
	v_mul_f32_e32 v214, v213, v213
	v_mov_b32_e32 v215, 0
	v_add_f32_e32 v107, v129, v243
	v_mul_f32_e32 v107, 0xbfb8aa3b, v107
	v_exp_f32_e32 v107, v107
	v_mov_b32_dpp v215, v214 quad_perm:[1,0,3,2] row_mask:0xf bank_mask:0xf
	v_fmac_f32_e32 v215, v213, v213
	v_fmac_f32_e32 v177, v117, v173
	v_add_f32_e32 v107, 1.0, v107
	v_add_f32_dpp v214, v215, v215 quad_perm:[2,3,0,1] row_mask:0xf bank_mask:0xf bound_ctrl:1
	v_mov_b32_e32 v216, 0
	s_nop 0
	v_add_f32_dpp v214, v214, v214 row_half_mirror row_mask:0xf bank_mask:0xf bound_ctrl:1
	s_nop 1
	v_add_f32_dpp v215, v214, v214 row_mirror row_mask:0xf bank_mask:0xf bound_ctrl:1
	v_rcp_f32_e32 v214, v107
	v_readlane_b32 s30, v215, 0
	v_readlane_b32 s35, v215, 16
	v_readlane_b32 s31, v215, 32
	v_add_f32_e32 v107, -1.0, v214
	v_fma_f32 v107, v126, v107, 1.0
	v_mul_f32_e32 v107, v175, v107
	v_mul_f32_e32 v175, v177, v107
	v_readlane_b32 s34, v215, 48
	v_mul_f32_e32 v215, v127, v175
	s_nop 1
	v_mov_b32_dpp v216, v215 quad_perm:[1,0,3,2] row_mask:0xf bank_mask:0xf
	v_fmac_f32_e32 v216, v127, v175
	v_mov_b32_e32 v215, 0
	s_nop 0
	v_add_f32_dpp v175, v216, v216 quad_perm:[2,3,0,1] row_mask:0xf bank_mask:0xf bound_ctrl:1
	s_nop 1
	v_add_f32_dpp v175, v175, v175 row_half_mirror row_mask:0xf bank_mask:0xf bound_ctrl:1
	s_nop 1
	v_mov_b32_dpp v215, v175 row_mirror row_mask:0xf bank_mask:0xf
	s_and_saveexec_b64 s[80:81], s[10:11]
	s_cbranch_execz .LBB0_606
	v_add_f32_e32 v175, v175, v215
	global_store_dword v[194:195], v175, off offset:1536
.LBB0_606:
	s_or_b64 exec, exec, s[80:81]
	v_mad_i64_i32 v[196:197], s[100:101], s99, v212, v[96:97]
	s_and_b64 s[100:101], s[44:45], exec
	s_cselect_b32 s99, s98, s84
	s_add_i32 s99, s99, s14
	s_or_b32 s98, s84, 6
	s_cmp_lt_u32 s98, s62
	s_cselect_b64 s[46:47], -1, 0
	global_load_short_d16_hi v149, v[196:197], off
	global_load_short_d16_hi v150, v[196:197], off offset:128
	global_load_short_d16_hi v151, v[196:197], off offset:256
	v_mul_f32_e32 v175, v122, v110
	v_fmac_f32_e32 v175, v121, v108
	v_fmac_f32_e32 v175, v123, v112
	ds_write_b32 v101, v175 offset:11008
	v_mul_f32_e32 v175, v116, v173
	v_fmac_f32_e32 v175, v124, v174
	v_mul_f32_e32 v174, v119, v111
	v_fmac_f32_e32 v174, v118, v109
	v_fmac_f32_e32 v174, v120, v113
	v_mul_f32_e32 v215, v125, v174
	v_mul_f32_e32 v216, v215, v215
	v_mov_b32_e32 v217, 0
	v_add_f32_e32 v109, v129, v245
	v_mul_f32_e32 v109, 0xbfb8aa3b, v109
	v_exp_f32_e32 v109, v109
	v_mov_b32_dpp v217, v216 quad_perm:[1,0,3,2] row_mask:0xf bank_mask:0xf
	v_fmac_f32_e32 v217, v215, v215
	v_fmac_f32_e32 v175, v117, v172
	v_add_f32_e32 v109, 1.0, v109
	v_add_f32_dpp v216, v217, v217 quad_perm:[2,3,0,1] row_mask:0xf bank_mask:0xf bound_ctrl:1
	v_mov_b32_e32 v218, 0
	s_nop 0
	v_add_f32_dpp v216, v216, v216 row_half_mirror row_mask:0xf bank_mask:0xf bound_ctrl:1
	s_nop 1
	v_add_f32_dpp v217, v216, v216 row_mirror row_mask:0xf bank_mask:0xf bound_ctrl:1
	v_rcp_f32_e32 v216, v109
	v_readlane_b32 s78, v217, 0
	v_readlane_b32 s90, v217, 16
	v_readlane_b32 s79, v217, 32
	v_add_f32_e32 v109, -1.0, v216
	v_fma_f32 v109, v126, v109, 1.0
	v_mul_f32_e32 v109, v174, v109
	v_mul_f32_e32 v174, v175, v109
	v_readlane_b32 s17, v217, 48
	v_mul_f32_e32 v217, v127, v174
	s_nop 1
	v_mov_b32_dpp v218, v217 quad_perm:[1,0,3,2] row_mask:0xf bank_mask:0xf
	v_fmac_f32_e32 v218, v127, v174
	v_mov_b32_e32 v217, 0
	s_nop 0
	v_add_f32_dpp v174, v218, v218 quad_perm:[2,3,0,1] row_mask:0xf bank_mask:0xf bound_ctrl:1
	s_nop 1
	v_add_f32_dpp v174, v174, v174 row_half_mirror row_mask:0xf bank_mask:0xf bound_ctrl:1
	s_nop 1
	v_mov_b32_dpp v217, v174 row_mirror row_mask:0xf bank_mask:0xf
	s_and_saveexec_b64 s[80:81], s[10:11]
	s_cbranch_execz .LBB0_608
	v_add_f32_e32 v174, v174, v217
	global_store_dword v[194:195], v174, off offset:2048
.LBB0_608:
	s_or_b64 exec, exec, s[80:81]
	v_mad_i64_i32 v[196:197], s[100:101], s99, v212, v[96:97]
	s_and_b64 s[100:101], s[46:47], exec
	s_cselect_b32 s99, s98, s84
	s_add_i32 s99, s99, s14
	s_or_b32 s98, s84, 7
	s_cmp_lt_u32 s98, s62
	s_cselect_b64 s[48:49], -1, 0
	global_load_short_d16_hi v152, v[196:197], off
	global_load_short_d16_hi v153, v[196:197], off offset:128
	global_load_short_d16_hi v154, v[196:197], off offset:256
	v_mul_f32_e32 v174, v122, v112
	v_fmac_f32_e32 v174, v121, v110
	v_fmac_f32_e32 v174, v123, v114
	ds_write_b32 v101, v174 offset:11264
	v_mul_f32_e32 v174, v116, v172
	v_fmac_f32_e32 v174, v124, v173
	v_mul_f32_e32 v173, v119, v113
	v_fmac_f32_e32 v173, v118, v111
	v_fmac_f32_e32 v173, v120, v115
	v_mul_f32_e32 v217, v125, v173
	v_mul_f32_e32 v218, v217, v217
	v_mov_b32_e32 v219, 0
	v_add_f32_e32 v111, v129, v247
	v_mul_f32_e32 v111, 0xbfb8aa3b, v111
	v_exp_f32_e32 v111, v111
	v_mov_b32_dpp v219, v218 quad_perm:[1,0,3,2] row_mask:0xf bank_mask:0xf
	v_fmac_f32_e32 v219, v217, v217
	v_fmac_f32_e32 v174, v117, v167
	v_add_f32_e32 v111, 1.0, v111
	v_add_f32_dpp v218, v219, v219 quad_perm:[2,3,0,1] row_mask:0xf bank_mask:0xf bound_ctrl:1
	v_mov_b32_e32 v220, 0
	s_nop 0
	v_add_f32_dpp v218, v218, v218 row_half_mirror row_mask:0xf bank_mask:0xf bound_ctrl:1
	s_nop 1
	v_add_f32_dpp v219, v218, v218 row_mirror row_mask:0xf bank_mask:0xf bound_ctrl:1
	v_rcp_f32_e32 v218, v111
	v_readlane_b32 s1, v219, 0
	v_readlane_b32 s92, v219, 16
	v_readlane_b32 s0, v219, 32
	v_add_f32_e32 v111, -1.0, v218
	v_fma_f32 v111, v126, v111, 1.0
	v_mul_f32_e32 v111, v173, v111
	v_mul_f32_e32 v173, v174, v111
	v_readlane_b32 s91, v219, 48
	v_mul_f32_e32 v219, v127, v173
	s_nop 1
	v_mov_b32_dpp v220, v219 quad_perm:[1,0,3,2] row_mask:0xf bank_mask:0xf
	v_fmac_f32_e32 v220, v127, v173
	v_mov_b32_e32 v219, 0
	s_nop 0
	v_add_f32_dpp v173, v220, v220 quad_perm:[2,3,0,1] row_mask:0xf bank_mask:0xf bound_ctrl:1
	s_nop 1
	v_add_f32_dpp v173, v173, v173 row_half_mirror row_mask:0xf bank_mask:0xf bound_ctrl:1
	s_nop 1
	v_mov_b32_dpp v219, v173 row_mirror row_mask:0xf bank_mask:0xf
	s_and_saveexec_b64 s[80:81], s[10:11]
	s_cbranch_execz .LBB0_610
	v_add_f32_e32 v173, v173, v219
	global_store_dword v[194:195], v173, off offset:2560
.LBB0_610:
	s_or_b64 exec, exec, s[80:81]
	v_mad_i64_i32 v[196:197], s[100:101], s99, v212, v[96:97]
	s_and_b64 s[100:101], s[48:49], exec
	s_cselect_b32 s99, s98, s84
	s_add_i32 s99, s99, s14
	s_add_i32 s98, s84, 8
	s_cmp_lt_u32 s98, s62
	s_cselect_b64 s[50:51], -1, 0
	global_load_short_d16_hi v155, v[196:197], off
	global_load_short_d16_hi v156, v[196:197], off offset:128
	global_load_short_d16_hi v157, v[196:197], off offset:256
	v_mul_f32_e32 v173, v122, v114
	v_mul_f32_e32 v220, v119, v115
	v_fmac_f32_e32 v173, v121, v112
	v_fmac_f32_e32 v220, v118, v113
	v_fmac_f32_e32 v173, v123, v164
	ds_write_b32 v101, v173 offset:11520
	v_mul_f32_e32 v173, v116, v167
	v_fmac_f32_e32 v220, v120, v168
	v_add_f32_e32 v113, v129, v249
	v_fmac_f32_e32 v173, v124, v172
	v_mul_f32_e32 v172, v125, v220
	v_mul_f32_e32 v113, 0xbfb8aa3b, v113
	v_mul_f32_e32 v219, v172, v172
	v_mov_b32_e32 v221, 0
	v_exp_f32_e32 v113, v113
	v_fmac_f32_e32 v173, v117, v169
	v_mov_b32_dpp v221, v219 quad_perm:[1,0,3,2] row_mask:0xf bank_mask:0xf
	v_fmac_f32_e32 v221, v172, v172
	v_add_f32_e32 v113, 1.0, v113
	v_mov_b32_e32 v222, 0
	v_add_f32_dpp v219, v221, v221 quad_perm:[2,3,0,1] row_mask:0xf bank_mask:0xf bound_ctrl:1
	s_nop 1
	v_add_f32_dpp v219, v219, v219 row_half_mirror row_mask:0xf bank_mask:0xf bound_ctrl:1
	s_nop 1
	v_add_f32_dpp v221, v219, v219 row_mirror row_mask:0xf bank_mask:0xf bound_ctrl:1
	v_rcp_f32_e32 v219, v113
	v_readlane_b32 s94, v221, 0
	v_readlane_b32 s97, v221, 16
	v_readlane_b32 s95, v221, 32
	v_add_f32_e32 v113, -1.0, v219
	v_fma_f32 v113, v126, v113, 1.0
	v_mul_f32_e32 v113, v220, v113
	v_mul_f32_e32 v220, v173, v113
	v_readlane_b32 s96, v221, 48
	v_mul_f32_e32 v221, v127, v220
	s_nop 1
	v_mov_b32_dpp v222, v221 quad_perm:[1,0,3,2] row_mask:0xf bank_mask:0xf
	v_fmac_f32_e32 v222, v127, v220
	v_mov_b32_e32 v221, 0
	s_nop 0
	v_add_f32_dpp v220, v222, v222 quad_perm:[2,3,0,1] row_mask:0xf bank_mask:0xf bound_ctrl:1
	s_nop 1
	v_add_f32_dpp v220, v220, v220 row_half_mirror row_mask:0xf bank_mask:0xf bound_ctrl:1
	s_nop 1
	v_mov_b32_dpp v221, v220 row_mirror row_mask:0xf bank_mask:0xf
	s_and_saveexec_b64 s[80:81], s[10:11]
	s_cbranch_execz .LBB0_612
	v_add_f32_e32 v222, v220, v221
	global_store_dword v[194:195], v222, off offset:3072
.LBB0_612:
	s_or_b64 exec, exec, s[80:81]
	v_mad_i64_i32 v[196:197], s[100:101], s99, v212, v[96:97]
	s_and_b64 s[100:101], s[50:51], exec
	s_cselect_b32 s99, s98, s84
	s_add_i32 s99, s99, s14
	global_load_short_d16_hi v158, v[196:197], off
	global_load_short_d16_hi v159, v[196:197], off offset:128
	global_load_short_d16_hi v160, v[196:197], off offset:256
	v_mul_f32_e32 v169, v116, v169
	v_fmac_f32_e32 v169, v124, v167
	v_mul_f32_e32 v220, v122, v164
	v_fmac_f32_e32 v169, v117, v171
	v_mul_f32_e32 v171, v119, v168
	v_fmac_f32_e32 v220, v121, v114
	v_fmac_f32_e32 v171, v118, v115
	v_fmac_f32_e32 v171, v120, v170
	v_mul_f32_e32 v168, v125, v171
	v_mul_f32_e32 v167, v168, v168
	v_mov_b32_e32 v170, 0
	v_add_f32_e32 v115, v129, v251
	v_mul_f32_e32 v115, 0xbfb8aa3b, v115
	v_exp_f32_e32 v115, v115
	v_mov_b32_dpp v170, v167 quad_perm:[1,0,3,2] row_mask:0xf bank_mask:0xf
	v_fmac_f32_e32 v170, v168, v168
	v_fmac_f32_e32 v220, v123, v166
	v_add_f32_e32 v115, 1.0, v115
	v_add_f32_dpp v167, v170, v170 quad_perm:[2,3,0,1] row_mask:0xf bank_mask:0xf bound_ctrl:1
	ds_write_b32 v101, v220 offset:11776
	v_mov_b32_e32 v220, 0
	v_add_f32_dpp v167, v167, v167 row_half_mirror row_mask:0xf bank_mask:0xf bound_ctrl:1
	s_nop 1
	v_add_f32_dpp v170, v167, v167 row_mirror row_mask:0xf bank_mask:0xf bound_ctrl:1
	v_rcp_f32_e32 v167, v115
	v_readlane_b32 s3, v170, 0
	v_readlane_b32 s64, v170, 16
	v_readlane_b32 s52, v170, 32
	v_add_f32_e32 v115, -1.0, v167
	v_fma_f32 v115, v126, v115, 1.0
	v_mul_f32_e32 v115, v171, v115
	v_readlane_b32 s53, v170, 48
	v_mul_f32_e32 v170, v169, v115
	v_mul_f32_e32 v171, v127, v170
	s_nop 1
	v_mov_b32_dpp v220, v171 quad_perm:[1,0,3,2] row_mask:0xf bank_mask:0xf
	v_fmac_f32_e32 v220, v127, v170
	v_mov_b32_e32 v171, 0
	s_nop 0
	v_add_f32_dpp v170, v220, v220 quad_perm:[2,3,0,1] row_mask:0xf bank_mask:0xf bound_ctrl:1
	s_nop 1
	v_add_f32_dpp v170, v170, v170 row_half_mirror row_mask:0xf bank_mask:0xf bound_ctrl:1
	s_nop 1
	v_mov_b32_dpp v171, v170 row_mirror row_mask:0xf bank_mask:0xf
	s_and_saveexec_b64 s[80:81], s[10:11]
	s_cbranch_execz .LBB0_614
	v_add_f32_e32 v220, v170, v171
	global_store_dword v[194:195], v220, off offset:3584
.LBB0_614:
	s_or_b64 exec, exec, s[80:81]
	v_mad_i64_i32 v[196:197], s[100:101], s99, v212, v[96:97]
	global_load_short_d16_hi v161, v[196:197], off
	global_load_short_d16_hi v162, v[196:197], off offset:128
	global_load_short_d16_hi v163, v[196:197], off offset:256
	v_mov_b32_e32 v171, s64
	v_add_f32_e32 v171, s3, v171
	v_add_f32_e32 v171, s52, v171
	v_add_f32_e32 v171, s53, v171
	v_add_f32_e32 v171, 0x2b8cbccc, v171
	v_rsq_f32_e32 v171, v171
	v_mul_f32_e32 v166, v122, v166
	v_fmac_f32_e32 v166, v121, v164
	v_add_f32_e32 v114, v128, v250
	v_mul_f32_e32 v164, v168, v171
	v_mov_b32_e32 v171, s90
	v_add_f32_e32 v171, s78, v171
	v_add_f32_e32 v171, s79, v171
	v_add_f32_e32 v171, s17, v171
	v_add_f32_e32 v171, 0x2b8cbccc, v171
	v_rsq_f32_e32 v171, v171
	v_add_f32_e32 v100, v128, v236
	v_mul_f32_e32 v114, 0xbfb8aa3b, v114
	v_mul_f32_e32 v100, 0xbfb8aa3b, v100
	v_mul_f32_e32 v171, v215, v171
	v_mul_f32_e32 v215, v171, v216
	v_mov_b32_e32 v216, s35
	v_add_f32_e32 v216, s30, v216
	v_add_f32_e32 v216, s31, v216
	v_add_f32_e32 v216, s34, v216
	v_add_f32_e32 v216, 0x2b8cbccc, v216
	v_rsq_f32_e32 v216, v216
	v_exp_f32_e32 v114, v114
	v_add_f32_e32 v112, v128, v248
	v_add_f32_e32 v102, v128, v238
	v_mul_f32_e32 v213, v213, v216
	v_mov_b32_e32 v216, s29
	v_add_f32_e32 v216, s26, v216
	v_add_f32_e32 v216, s27, v216
	v_add_f32_e32 v216, s28, v216
	v_add_f32_e32 v216, 0x2b8cbccc, v216
	v_rsq_f32_e32 v216, v216
	v_exp_f32_e32 v100, v100
	v_fmac_f32_e32 v166, v123, v165
	v_mov_b32_e32 v165, s92
	v_mul_f32_e32 v202, v202, v216
	v_mov_b32_e32 v216, s25
	v_add_f32_e32 v216, s23, v216
	v_add_f32_e32 v216, s24, v216
	v_add_f32_e32 v216, s22, v216
	v_add_f32_e32 v216, 0x2b8cbccc, v216
	v_rsq_f32_e32 v216, v216
	v_mul_f32_e32 v112, 0xbfb8aa3b, v112
	v_mul_f32_e32 v102, 0xbfb8aa3b, v102
	v_mov_b32_e32 v170, s97
	v_mul_f32_e32 v180, v180, v216
	v_mov_b32_e32 v216, s20
	v_add_f32_e32 v216, s85, v216
	v_add_f32_e32 v165, s1, v165
	v_exp_f32_e32 v112, v112
	v_add_f32_e32 v110, v128, v246
	v_add_f32_e32 v104, v128, v240
	v_add_f32_e32 v216, s18, v216
	v_exp_f32_e32 v102, v102
	v_add_f32_e32 v170, s94, v170
	v_add_f32_e32 v165, s0, v165
	v_mul_f32_e32 v110, 0xbfb8aa3b, v110
	v_mul_f32_e32 v104, 0xbfb8aa3b, v104
	v_add_f32_e32 v216, s19, v216
	v_add_f32_e32 v170, s95, v170
	v_add_f32_e32 v114, 1.0, v114
	v_add_f32_e32 v165, s91, v165
	v_exp_f32_e32 v110, v110
	v_exp_f32_e32 v104, v104
	v_add_f32_e32 v216, 0x2b8cbccc, v216
	v_add_f32_e32 v100, 1.0, v100
	v_add_f32_e32 v170, s96, v170
	v_rcp_f32_e32 v114, v114
	v_add_f32_e32 v165, 0x2b8cbccc, v165
	v_rsq_f32_e32 v216, v216
	v_rcp_f32_e32 v100, v100
	v_add_f32_e32 v170, 0x2b8cbccc, v170
	v_rsq_f32_e32 v165, v165
	v_add_f32_e32 v112, 1.0, v112
	v_add_f32_e32 v102, 1.0, v102
	v_rsq_f32_e32 v170, v170
	v_rcp_f32_e32 v112, v112
	v_rcp_f32_e32 v102, v102
	v_add_f32_e32 v110, 1.0, v110
	v_add_f32_e32 v104, 1.0, v104
	v_mul_f32_e32 v114, 0x3f6002cd, v114
	v_rcp_f32_e32 v110, v110
	v_rcp_f32_e32 v104, v104
	v_mul_f32_e32 v178, v178, v216
	v_mul_f32_e32 v100, 0x3f6002cd, v100
	v_mul_f32_e32 v165, v217, v165
	v_mul_f32_e32 v183, v178, v183
	v_mul_f32_e32 v167, v164, v167
	v_cndmask_b32_e64 v216, v114, v100, s[12:13]
	v_mul_f32_e32 v170, v172, v170
	v_mul_f32_e32 v168, v165, v218
	v_mul_f32_e32 v112, 0x3f6002cd, v112
	v_mul_f32_e32 v102, 0x3f6002cd, v102
	v_cndmask_b32_e64 v217, v164, v178, s[12:13]
	v_cndmask_b32_e64 v218, v167, v183, s[12:13]
	v_cndmask_b32_e64 v220, v169, v176, s[12:13]
	v_cndmask_b32_e64 v100, v100, v114, s[12:13]
	v_cndmask_b32_e64 v114, v178, v164, s[12:13]
	v_cndmask_b32_e64 v164, v183, v167, s[12:13]
	v_cndmask_b32_e64 v167, v176, v169, s[12:13]
	v_add_f32_e32 v169, 0, v216
	v_mul_f32_e32 v172, v170, v219
	v_cndmask_b32_e64 v221, v112, v102, s[12:13]
	v_cndmask_b32_e64 v222, v170, v180, s[12:13]
	v_cndmask_b32_e64 v102, v102, v112, s[12:13]
	v_cndmask_b32_e64 v112, v180, v170, s[12:13]
	v_exp_f32_e32 v170, v169
	v_mul_f32_e32 v110, 0x3f6002cd, v110
	v_mul_f32_e32 v203, v202, v203
	v_mul_f32_e32 v184, v180, v184
	v_mul_f32_e32 v104, 0x3f6002cd, v104
	v_cndmask_b32_e64 v223, v172, v184, s[12:13]
	v_cndmask_b32_e64 v226, v110, v104, s[12:13]
	v_cndmask_b32_e64 v227, v165, v202, s[12:13]
	v_cndmask_b32_e64 v228, v168, v203, s[12:13]
	v_cndmask_b32_e64 v104, v104, v110, s[12:13]
	v_cndmask_b32_e64 v110, v202, v165, s[12:13]
	v_cndmask_b32_e64 v165, v203, v168, s[12:13]
	v_cndmask_b32_e64 v168, v184, v172, s[12:13]
	v_exp_f32_e64 v172, -v169
	v_readlane_b32 s0, v253, 22
	v_cndmask_b32_e64 v224, v113, v103, s[12:13]
	v_cndmask_b32_e64 v225, v173, v179, s[12:13]
	v_cndmask_b32_e64 v103, v103, v113, s[12:13]
	v_cndmask_b32_e64 v113, v179, v173, s[12:13]
	v_add_u32_e32 v173, s0, v101
	v_readlane_b32 s0, v253, 23
	v_cndmask_b32_e64 v219, v115, v182, s[12:13]
	v_cndmask_b32_e64 v229, v111, v105, s[12:13]
	v_cndmask_b32_e64 v230, v174, v181, s[12:13]
	v_cndmask_b32_e64 v105, v105, v111, s[12:13]
	v_cndmask_b32_e64 v111, v181, v174, s[12:13]
	ds_write_b32 v173, v217
	v_mul_f32_e32 v173, v218, v170
	v_add_u32_e32 v174, s0, v101
	v_readlane_b32 s0, v253, 24
	ds_write_b32 v174, v173
	v_mul_f32_e32 v170, v170, v219
	v_add_u32_e32 v173, s0, v101
	v_readlane_b32 s0, v253, 25
	ds_write_b32 v173, v170
	v_mul_f32_e32 v170, v220, v172
	v_add_u32_e32 v173, s0, v101
	v_add_f32_e32 v169, v221, v169
	v_add_f32_e32 v108, v128, v244
	v_add_f32_e32 v106, v128, v242
	ds_write_b32 v173, v170
	v_exp_f32_e32 v173, v169
	v_mul_f32_e32 v108, 0xbfb8aa3b, v108
	v_mul_f32_e32 v106, 0xbfb8aa3b, v106
	v_exp_f32_e32 v108, v108
	v_exp_f32_e32 v106, v106
	v_exp_f32_e64 v170, -v169
	v_readlane_b32 s0, v253, 26
	v_mul_f32_e32 v172, v222, v172
	v_add_f32_e32 v108, 1.0, v108
	v_add_u32_e32 v174, s0, v101
	v_readlane_b32 s0, v253, 27
	ds_write_b32 v174, v172
	v_mul_f32_e32 v172, v223, v173
	v_add_u32_e32 v174, s0, v101
	v_readlane_b32 s0, v253, 28
	ds_write_b32 v174, v172
	v_mul_f32_e32 v172, v224, v173
	v_add_u32_e32 v173, s0, v101
	v_readlane_b32 s0, v253, 29
	v_add_f32_e32 v106, 1.0, v106
	ds_write_b32 v173, v172
	v_mul_f32_e32 v172, v225, v170
	v_add_u32_e32 v173, s0, v101
	v_add_f32_e32 v169, v226, v169
	v_rcp_f32_e32 v108, v108
	v_rcp_f32_e32 v106, v106
	ds_write_b32 v173, v172
	v_exp_f32_e32 v173, v169
	v_exp_f32_e64 v172, -v169
	v_readlane_b32 s0, v253, 30
	v_mul_f32_e32 v170, v227, v170
	v_mul_f32_e32 v108, 0x3f6002cd, v108
	v_add_u32_e32 v174, s0, v101
	v_readlane_b32 s0, v253, 31
	v_mul_f32_e32 v106, 0x3f6002cd, v106
	ds_write_b32 v174, v170
	v_mul_f32_e32 v170, v228, v173
	v_add_u32_e32 v174, s0, v101
	v_readlane_b32 s0, v253, 32
	v_cndmask_b32_e64 v231, v108, v106, s[12:13]
	ds_write_b32 v174, v170
	v_mul_f32_e32 v170, v229, v173
	v_add_u32_e32 v173, s0, v101
	v_readlane_b32 s0, v253, 33
	ds_write_b32 v173, v170
	v_mul_f32_e32 v170, v230, v172
	v_add_u32_e32 v173, s0, v101
	v_add_f32_e32 v169, v231, v169
	ds_write_b32 v173, v170
	v_exp_f32_e32 v173, v169
	v_mul_f32_e32 v214, v213, v214
	v_cndmask_b32_e64 v232, v171, v213, s[12:13]
	v_exp_f32_e64 v170, -v169
	v_readlane_b32 s0, v253, 34
	v_cndmask_b32_e64 v233, v215, v214, s[12:13]
	v_mul_f32_e32 v172, v232, v172
	v_add_u32_e32 v174, s0, v101
	v_cndmask_b32_e64 v234, v109, v107, s[12:13]
	ds_write_b32 v174, v172
	v_mul_f32_e32 v172, v233, v173
	v_add_u32_e32 v174, s65, v101
	v_cndmask_b32_e64 v235, v175, v177, s[12:13]
	v_cndmask_b32_e64 v106, v106, v108, s[12:13]
	ds_write_b32 v174, v172
	v_mul_f32_e32 v172, v234, v173
	v_add_u32_e32 v173, s33, v101
	ds_write_b32 v173, v172
	v_mul_f32_e32 v172, v235, v170
	v_add_u32_e32 v173, s70, v101
	v_add_f32_e32 v106, v106, v169
	ds_write_b32 v173, v172
	v_exp_f32_e32 v172, v106
	v_cndmask_b32_e64 v108, v213, v171, s[12:13]
	v_exp_f32_e64 v169, -v106
	v_cndmask_b32_e64 v171, v214, v215, s[12:13]
	v_mul_f32_e32 v108, v108, v170
	v_add_u32_e32 v170, s71, v101
	v_cndmask_b32_e64 v107, v107, v109, s[12:13]
	ds_write_b32 v170, v108
	v_mul_f32_e32 v108, v171, v172
	v_add_u32_e32 v170, s66, v101
	v_cndmask_b32_e64 v109, v177, v175, s[12:13]
	ds_write_b32 v170, v108
	v_mul_f32_e32 v107, v107, v172
	v_add_u32_e32 v108, s67, v101
	ds_write_b32 v108, v107
	v_mul_f32_e32 v107, v109, v169
	v_add_u32_e32 v108, s93, v101
	v_add_f32_e32 v104, v104, v106
	ds_write_b32 v108, v107
	v_exp_f32_e32 v107, v104
	v_exp_f32_e64 v106, -v104
	v_mul_f32_e32 v108, v110, v169
	v_add_u32_e32 v109, s2, v101
	ds_write_b32 v109, v108
	v_mul_f32_e32 v108, v165, v107
	v_mul_f32_e32 v105, v105, v107
	v_add_u32_e32 v107, s89, v101
	ds_write_b32 v107, v105
	v_mul_f32_e32 v105, v111, v106
	v_add_u32_e32 v107, s76, v101
	v_add_f32_e32 v102, v102, v104
	ds_write_b32 v107, v105
	v_exp_f32_e32 v105, v102
	v_exp_f32_e64 v104, -v102
	v_add_f32_e32 v100, v100, v102
	v_mul_f32_e32 v106, v112, v106
	v_add_u32_e32 v107, s77, v101
	v_exp_f32_e64 v102, -v100
	v_exp_f32_e32 v100, v100
	ds_write_b32 v107, v106
	v_mul_f32_e32 v106, v168, v105
	v_mul_f32_e32 v103, v103, v105
	v_add_u32_e32 v105, s55, v101
	ds_write_b32 v105, v103
	v_mul_f32_e32 v103, v113, v104
	v_add_u32_e32 v105, s72, v101
	ds_write_b32 v105, v103
	v_mul_f32_e32 v103, v114, v104
	v_add_u32_e32 v104, s73, v101
	v_cndmask_b32_e64 v115, v182, v115, s[12:13]
	v_add_u32_e32 v109, s87, v101
	v_add_u32_e32 v107, s54, v101
	ds_write_b32 v104, v103
	v_mul_f32_e32 v103, v164, v100
	v_add_u32_e32 v104, s56, v101
	s_waitcnt vmcnt(36)
	s_nop 0
	s_nop 0
	ds_write_b32 v109, v108
	ds_write_b32 v107, v106
	ds_write_b32 v104, v103
	v_mul_f32_e32 v100, v115, v100
	v_add_u32_e32 v103, s57, v101
	v_mul_f32_e32 v92, 0xc038aa3b, v92
	v_mul_f32_e32 v88, 0xc038aa3b, v88
	ds_write_b32 v103, v100
	v_exp_f32_e32 v92, v92
	v_exp_f32_e32 v103, v88
	s_nop 0
	s_nop 0
	v_mul_f32_e32 v93, 0xc038aa3b, v93
	v_mul_f32_e32 v89, 0xc038aa3b, v89
	v_add_f32_e32 v88, 1.0, v92
	v_add_f32_e32 v92, 1.0, v103
	v_exp_f32_e32 v93, v93
	v_exp_f32_e32 v103, v89
	s_nop 0
	s_nop 0
	s_nop 0
	v_mul_f32_e32 v94, 0xc038aa3b, v94
	v_mul_f32_e32 v90, 0xc038aa3b, v90
	v_mul_f32_e32 v95, 0xc038aa3b, v95
	v_add_f32_e32 v89, 1.0, v93
	v_add_f32_e32 v93, 1.0, v103
	v_exp_f32_e32 v94, v94
	v_exp_f32_e32 v103, v90
	v_exp_f32_e32 v95, v95
	s_waitcnt vmcnt(32)
	s_nop 0
	s_nop 0
	v_mul_f32_e32 v81, 0xc038aa3b, v81
	v_mul_f32_e32 v77, 0xc038aa3b, v77
	s_nop 0
	v_cvt_pk_bf16_f32 v84, v84, v85
	v_cvt_pk_bf16_f32 v85, v86, v87
	v_exp_f32_e32 v81, v81
	v_exp_f32_e32 v86, v77
	v_mul_f32_e32 v91, 0xc038aa3b, v91
	v_add_f32_e32 v90, 1.0, v94
	v_add_f32_e32 v94, 1.0, v103
	v_exp_f32_e32 v103, v91
	v_add_f32_e32 v91, 1.0, v95
	s_nop 0
	s_nop 0
	v_rcp_f32_e32 v88, v88
	v_rcp_f32_e32 v92, v92
	v_rcp_f32_e32 v89, v89
	v_rcp_f32_e32 v93, v93
	v_rcp_f32_e32 v90, v90
	v_rcp_f32_e32 v91, v91
	v_mul_f32_e32 v82, 0xc038aa3b, v82
	v_mul_f32_e32 v78, 0xc038aa3b, v78
	v_add_f32_e32 v77, 1.0, v81
	v_add_f32_e32 v81, 1.0, v86
	v_exp_f32_e32 v82, v82
	v_exp_f32_e32 v86, v78
	s_nop 0
	s_nop 0
	s_nop 0
	s_nop 0
	v_pk_fma_f32 v[88:89], v[88:89], 2.0, -1.0 op_sel_hi:[1,0,0]
	v_pk_fma_f32 v[92:93], v[92:93], 2.0, -1.0 op_sel_hi:[1,0,0]
	v_pk_fma_f32 v[90:91], v[90:91], 2.0, -1.0 op_sel_hi:[1,0,0]
	v_mul_f32_e32 v80, 0xc038aa3b, v80
	v_mul_f32_e32 v76, 0xc038aa3b, v76
	v_mul_f32_e32 v83, 0xc038aa3b, v83
	v_mul_f32_e32 v79, 0xc038aa3b, v79
	v_add_f32_e32 v95, 1.0, v103
	v_cvt_pk_bf16_f32 v88, v88, v89
	v_cvt_pk_bf16_f32 v89, v90, v91
	v_cvt_pk_bf16_f32 v90, v92, v93
	v_exp_f32_e32 v80, v80
	v_exp_f32_e32 v92, v76
	v_add_f32_e32 v78, 1.0, v82
	v_add_f32_e32 v82, 1.0, v86
	v_exp_f32_e32 v83, v83
	v_exp_f32_e32 v86, v79
	v_rcp_f32_e32 v94, v94
	v_rcp_f32_e32 v95, v95
	v_add_f32_e32 v76, 1.0, v80
	v_add_f32_e32 v80, 1.0, v92
	v_add_f32_e32 v79, 1.0, v83
	v_add_f32_e32 v83, 1.0, v86
	v_pk_fma_f32 v[94:95], v[94:95], 2.0, -1.0 op_sel_hi:[1,0,0]
	v_rcp_f32_e32 v76, v76
	v_rcp_f32_e32 v80, v80
	v_rcp_f32_e32 v77, v77
	v_rcp_f32_e32 v81, v81
	v_rcp_f32_e32 v78, v78
	v_rcp_f32_e32 v82, v82
	v_rcp_f32_e32 v79, v79
	v_rcp_f32_e32 v83, v83
	v_cvt_pk_bf16_f32 v91, v94, v95
	v_cvt_pk_bf16_f32 v86, v68, v69
	v_cvt_pk_bf16_f32 v87, v70, v71
	v_pk_fma_f32 v[76:77], v[76:77], 2.0, -1.0 op_sel_hi:[1,0,0]
	v_pk_fma_f32 v[80:81], v[80:81], 2.0, -1.0 op_sel_hi:[1,0,0]
	v_pk_fma_f32 v[78:79], v[78:79], 2.0, -1.0 op_sel_hi:[1,0,0]
	v_pk_fma_f32 v[82:83], v[82:83], 2.0, -1.0 op_sel_hi:[1,0,0]
	v_cvt_pk_bf16_f32 v76, v76, v77
	v_cvt_pk_bf16_f32 v77, v78, v79
	v_cvt_pk_bf16_f32 v78, v80, v81
	v_cvt_pk_bf16_f32 v79, v82, v83
	s_waitcnt vmcnt(30)
	v_cvt_pk_bf16_f32 v68, v72, v73
	v_cvt_pk_bf16_f32 v69, v74, v75
	v_cvt_pk_bf16_f32 v70, v64, v65
	v_cvt_pk_bf16_f32 v71, v66, v67
	v_mfma_f32_16x16x32_bf16 v[80:83], v[88:91], v[0:3], 0
	v_mul_f32_e32 v100, v167, v102
	v_add_u32_e32 v104, s58, v101
	ds_write_b32 v104, v100
	ds_write2st64_b32 v101, v102, v166 offset1:47
	v_mfma_f32_16x16x32_bf16 v[64:67], v[84:87], v[32:35], 0
	s_waitcnt lgkmcnt(0)
	v_mfma_f32_16x16x32_bf16 v[80:83], v[76:79], v[16:19], v[80:83]
	v_mfma_f32_16x16x32_bf16 v[64:67], v[68:71], v[36:39], v[64:67]
	s_and_saveexec_b64 s[80:81], s[8:9]
	s_cbranch_execz .LBB0_616
	s_nop 5
	ds_write2st64_b32 v209, v80, v64 offset1:1
	ds_write2st64_b32 v209, v81, v65 offset0:2 offset1:3
	ds_write2st64_b32 v209, v82, v66 offset0:4 offset1:5
	ds_write2st64_b32 v209, v83, v67 offset0:6 offset1:7
